# v20 + decode item start: Q-fragment loads, page-table row load and pointer loads issued together (were three dependent round trips); Q fragments written to LDS after the single wait
# baseline (speedup 1.0000x reference)
; #define LAS __attribute__((address_space(3)))
; __device__ __forceinline__ void decode_unit(int item, const float* ck, const float* cv, const int* pt, const bf16* QB, const float* ksamp, const float* vsamp, bf16* MIX_unused_, LAS unsigned char* lds, const LAS float* BL, float lam, float* PART, gu32* dcnt, bf16* MIX, gu32* rdy4) {
;     const int b = item >> 2, qtr = item & 3;
;     const int tid = threadIdx.x, lane = tid & 63, n = lane & 15, q = lane >> 4; const int wid = __builtin_amdgcn_readfirstlane(tid >> 6), h = wid & 3, kh = wid >> 2;
;     const LAS float* BLh = BL + h * 128;
;     LAS bf16x8* qfl = (LAS bf16x8*)(lds + 40960 + wid * 4096) + lane;
; #pragma unroll
;     for (int mp = 0; mp < 2; ++mp)
; #pragma unroll
;         for (int ks = 0; ks < 2; ++ks) { const int tk = n - 4 * mp; const bool ok = tk >= 0 && tk < 4;
;             const v4u w = ok ? *(const v4u*)(QB + (size_t)(MP + 4 * b + tk) * 512 + h * 128 + mp * 64 + 32 * ks + 8 * q) : (v4u){0u, 0u, 0u, 0u}; qfl[(mp * 2 + ks) * 64] = __builtin_bit_cast(bf16x8, w); }
;     asm volatile("s_waitcnt lgkmcnt(0)" ::: "memory");
;     const int tok = n & 3;
;     f32x4 O[8];
; #pragma unroll
;     for (int c = 0; c < 8; ++c) O[c] = (f32x4){0.f, 0.f, 0.f, 0.f};
;     float lsum = 0.f;
;     const int NIT = (kh == 0 && qtr == 3) ? 9 : 8;
;     f32x4 kr[2][2][2][2], vr[8][2];
;     const int vkey0 = 4 * q;
;     ...
;     const int ptv = pt[b * NPAGES + (lane & 15)];
;     const float* kbase; const float* vbase; int key0; bool isnew;
;     DEC_BASES(0, kbase, vbase, key0, isnew);
;     DEC_LOADK(kbase, isnew);
.LBB0_658:
	s_andn2_b64 vcc, exec, s[20:21]
	s_cbranch_vccnz .LBB0_610
	s_cmpk_lt_i32 s64, 0x200
	s_mov_b64 s[18:19], -1
	s_cbranch_scc0 .LBB0_697
	s_ashr_i32 s18, s64, 31
	s_lshr_b32 s18, s18, 23
	s_add_i32 s18, s64, s18
	s_and_b32 s18, s18, 0xfffffe00
	s_sub_i32 s89, s64, s18
	v_readfirstlane_b32 s67, v0
	s_bfe_u32 s88, s67, 0x20006
	s_and_b32 s64, s89, -4
	s_add_i32 s66, s64, 0x4000
	s_lshl_b32 s18, s88, 8
	s_add_u32 s18, s0, s18
	s_addc_u32 s19, s1, 0
	s_load_dwordx4 s[20:23], s[24:25], 0x10
	s_load_dwordx2 s[68:69], s[24:25], 0x20
	s_load_dwordx2 s[70:71], s[24:25], 0xb0
	v_mov_b32_e32 v100, 0
	v_mov_b32_e32 v101, 0
	v_mov_b32_e32 v102, 0
	v_mov_b32_e32 v103, 0
	v_mov_b32_e32 v104, 0
	v_mov_b32_e32 v105, 0
	v_mov_b32_e32 v106, 0
	v_mov_b32_e32 v107, 0
	v_mov_b32_e32 v108, 0
	v_mov_b32_e32 v109, 0
	v_mov_b32_e32 v110, 0
	v_mov_b32_e32 v111, 0
	v_mov_b32_e32 v112, 0
	v_mov_b32_e32 v113, 0
	v_mov_b32_e32 v114, 0
	v_mov_b32_e32 v115, 0
	s_and_saveexec_b64 vcc, s[10:11]
	v_or_b32_e32 v98, s66, v194
	v_lshlrev_b64 v[116:117], 10, v[98:99]
	v_lshl_add_u64 v[116:117], s[18:19], 0, v[116:117]
	v_lshlrev_b32_e32 v98, 1, v196
	v_lshl_add_u64 v[116:117], v[116:117], 0, v[98:99]
	global_load_dwordx4 v[100:103], v[116:117], off
	global_load_dwordx4 v[104:107], v[116:117], off offset:64
	s_or_b64 exec, exec, vcc
	s_and_saveexec_b64 vcc, s[12:13]
	v_or_b32_e32 v98, s66, v222
	v_lshlrev_b64 v[118:119], 10, v[98:99]
	v_lshl_add_u64 v[118:119], s[18:19], 0, v[118:119]
	v_lshlrev_b32_e32 v98, 1, v196
	v_lshl_add_u64 v[118:119], v[118:119], 0, v[98:99]
	global_load_dwordx4 v[108:111], v[118:119], off offset:128
	global_load_dwordx4 v[112:115], v[118:119], off offset:192
	s_or_b64 exec, exec, vcc
	s_lshr_b32 s87, s67, 6
	s_lshl_b32 s65, s87, 12
	v_lshl_add_u32 v3, v230, 4, 0
	v_add_u32_e32 v213, s65, v3
	s_lshl_b32 s28, s88, 7
	s_mov_b32 s91, 0
	s_ashr_i32 s18, s89, 2
	v_lshl_or_b32 v2, s18, 4, v194
	s_waitcnt lgkmcnt(0)
	v_mov_b32_e32 v10, s68
	v_mov_b32_e32 v11, s69
	v_ashrrev_i32_e32 v3, 31, v2
	v_lshl_add_u64 v[2:3], v[2:3], 2, v[10:11]
	global_load_dword v217, v[2:3], off
	s_lshl_b32 s77, s28, 2
	s_add_i32 s90, s77, 0
	s_lshr_b32 s19, s67, 8
	s_and_b32 s76, s89, 3
	s_add_i32 s90, s90, 0x20200
	s_cmpk_lt_u32 s67, 0x100
	s_cselect_b64 s[68:69], -1, 0
	s_cmp_eq_u32 s76, 3
	s_cselect_b64 s[72:73], -1, 0
	s_lshl_b32 s65, s76, 4
	s_add_i32 s80, s19, s65
	s_and_b64 s[74:75], s[72:73], s[68:69]
	s_lshr_b32 s72, s80, 2
	s_lshl_b32 s78, s67, 6
	s_and_b32 s65, s78, 0xc000
	v_mov_b32_e32 v221, v99
	v_mov_b32_e32 v215, 0
	v_mov_b32_e32 v30, 0
	v_mov_b32_e32 v31, v215
	v_mov_b32_e32 v32, v215
	v_mov_b32_e32 v33, v215
	v_mov_b32_e32 v26, 0
	v_mov_b32_e32 v27, v215
	v_mov_b32_e32 v28, v215
	v_mov_b32_e32 v29, v215
	v_mov_b32_e32 v22, 0
	v_mov_b32_e32 v23, v215
	v_mov_b32_e32 v24, v215
	v_mov_b32_e32 v25, v215
	v_mov_b32_e32 v18, 0
	v_mov_b32_e32 v19, v215
	v_mov_b32_e32 v20, v215
	v_mov_b32_e32 v21, v215
	v_mov_b32_e32 v14, 0
	v_mov_b32_e32 v15, v215
	v_mov_b32_e32 v16, v215
	v_mov_b32_e32 v17, v215
	v_mov_b32_e32 v12, v215
	v_mov_b32_e32 v13, v215
	s_waitcnt vmcnt(0)
	ds_write_b128 v213, v[100:103] offset:40960
	ds_write_b128 v213, v[104:107] offset:41984
	ds_write_b128 v213, v[108:111] offset:43008
	ds_write_b128 v213, v[112:115] offset:44032
	v_readlane_b32 s72, v217, s72
	s_ashr_i32 s73, s72, 31
	s_lshl_b64 s[72:73], s[72:73], 16
	s_or_b32 s72, s72, s65
	s_or_b64 s[72:73], s[72:73], s[28:29]
	s_lshl_b64 s[72:73], s[72:73], 2
	s_add_u32 s78, s20, s72
	s_addc_u32 s79, s21, s73
	v_lshl_add_u64 v[2:3], v[196:197], 2, s[78:79]
	v_lshl_add_u64 v[2:3], v[2:3], 0, v[220:221]
	s_mov_b64 s[78:79], 0x8000
	v_lshl_add_u64 v[4:5], v[2:3], 0, s[78:79]
	s_mov_b32 s65, 0x8000
	s_mov_b64 s[78:79], 0x8080
	v_add_co_u32_e32 v6, vcc, s65, v2
	v_lshl_add_u64 v[8:9], v[2:3], 0, s[78:79]
	s_mov_b64 s[78:79], 0x8100
	v_addc_co_u32_e32 v7, vcc, 0, v3, vcc
	v_lshl_add_u64 v[10:11], v[2:3], 0, s[78:79]
	s_mov_b64 s[78:79], 0x8180
	global_load_dwordx4 v[58:61], v[2:3], off offset:16
	global_load_dwordx4 v[62:65], v[2:3], off
	global_load_dwordx4 v[50:53], v[2:3], off offset:144
	global_load_dwordx4 v[54:57], v[2:3], off offset:128
	global_load_dwordx4 v[42:45], v[2:3], off offset:272
	global_load_dwordx4 v[46:49], v[2:3], off offset:256
	global_load_dwordx4 v[34:37], v[2:3], off offset:400
	global_load_dwordx4 v[38:41], v[2:3], off offset:384
	v_lshl_add_u64 v[2:3], v[2:3], 0, s[78:79]
	global_load_dwordx4 v[94:97], v[6:7], off
	global_load_dwordx4 v[86:89], v[4:5], off offset:16
	global_load_dwordx4 v[90:93], v[6:7], off offset:128
	global_load_dwordx4 v[70:73], v[6:7], off offset:256
	global_load_dwordx4 v[82:85], v[8:9], off offset:16
	global_load_dwordx4 v[66:69], v[6:7], off offset:384
	global_load_dwordx4 v[78:81], v[10:11], off offset:16
	global_load_dwordx4 v[74:77], v[2:3], off offset:16
	s_add_u32 s78, s22, s72
	s_addc_u32 s79, s23, s73
	s_ashr_i32 s65, s64, 31
	s_lshl_b64 s[72:73], s[64:65], 11
	s_lshl_b32 s97, s80, 5
	s_or_b32 s72, s72, s77
	s_add_u32 s72, s70, s72
	s_addc_u32 s73, s71, s73
	s_add_u32 s70, s72, 0x828b000
	s_addc_u32 s71, s73, 0
	s_add_u32 s72, s72, 0x838b000
	s_addc_u32 s73, s73, 0
	s_and_b64 s[74:75], s[74:75], exec
	s_movk_i32 s74, 0x1c0
	s_cselect_b32 s92, 0x200, s74
	s_lshl_b32 s74, s76, 9
	s_lshl_b32 s75, s19, 5
	s_add_i32 s93, s74, s75
	s_add_i32 s94, s80, 2
	s_add_i32 s93, s93, 64
	s_lshl_b32 s95, s94, 14
	s_mov_b64 s[76:77], 0
	v_mov_b32_e32 v10, 0
	v_mov_b32_e32 v11, v215
	v_mov_b32_e32 v6, 0
	v_mov_b32_e32 v7, v215
	v_mov_b32_e32 v8, v215
	v_mov_b32_e32 v9, v215
	v_mov_b32_e32 v2, 0
	v_mov_b32_e32 v3, v215
	v_mov_b32_e32 v4, v215
	v_mov_b32_e32 v5, v215
